# adds: merged vmcnt+lgkmcnt waits before the pre-MFMA barrier; second-buffer B fragments read via immediate offsets (no per-iteration VALU address adds)
# baseline (speedup 1.0000x reference)
.LBB0_126:
	ds_read_b128 v[130:133], v176
	ds_read_b128 v[134:137], v176 offset:1024
	ds_read_b128 v[170:173], v176 offset:2048
	ds_read_b128 v[180:183], v176 offset:3072
	ds_read_b128 v[184:187], v177
	ds_read_b128 v[188:191], v177 offset:1024
	ds_read_b128 v[192:195], v177 offset:2048
	ds_read_b128 v[198:201], v177 offset:3072
	s_add_u32 s14, s8, 0xfff00080
	s_addc_u32 s15, s9, -1
	s_cmp_eq_u32 s29, 60
	s_cselect_b32 s19, s11, s15
	s_cselect_b32 s18, s13, s14
	s_cselect_b32 s15, s17, s28
	s_cselect_b32 s14, s20, s21
	s_add_i32 m0, s73, 0xc000
	ds_read_b128 v[202:205], v178
	ds_read_b128 v[206:209], v178 offset:1024
	ds_read_b128 v[210:213], v178 offset:2048
	ds_read_b128 v[214:217], v178 offset:3072
	ds_read_b128 v[218:221], v178 offset:4096
	ds_read_b128 v[222:225], v178 offset:5120
	ds_read_b128 v[226:229], v178 offset:6144
	ds_read_b128 v[230:233], v178 offset:7168
	global_load_lds_dwordx4 v160, s[8:9]
	s_add_i32 m0, s73, 0xe000
	s_nop 0
	global_load_lds_dwordx4 v162, s[8:9]
	s_waitcnt vmcnt(8) lgkmcnt(0)
	s_setprio 1
	s_barrier
	v_mfma_f32_16x16x32_bf16 v[126:129], v[130:133], v[202:205], v[126:129]
	v_mfma_f32_16x16x32_bf16 v[122:125], v[170:173], v[202:205], v[122:125]
	v_mfma_f32_16x16x32_bf16 v[110:113], v[130:133], v[210:213], v[110:113]
	v_mfma_f32_16x16x32_bf16 v[106:109], v[170:173], v[210:213], v[106:109]
	v_mfma_f32_16x16x32_bf16 v[94:97], v[130:133], v[218:221], v[94:97]
	v_mfma_f32_16x16x32_bf16 v[90:93], v[170:173], v[218:221], v[90:93]
	v_mfma_f32_16x16x32_bf16 v[78:81], v[130:133], v[226:229], v[78:81]
	v_mfma_f32_16x16x32_bf16 v[74:77], v[170:173], v[226:229], v[74:77]
	v_mfma_f32_16x16x32_bf16 v[126:129], v[134:137], v[206:209], v[126:129]
	v_mfma_f32_16x16x32_bf16 v[122:125], v[180:183], v[206:209], v[122:125]
	v_mfma_f32_16x16x32_bf16 v[110:113], v[134:137], v[214:217], v[110:113]
	v_mfma_f32_16x16x32_bf16 v[106:109], v[180:183], v[214:217], v[106:109]
	v_mfma_f32_16x16x32_bf16 v[94:97], v[134:137], v[222:225], v[94:97]
	v_mfma_f32_16x16x32_bf16 v[90:93], v[180:183], v[222:225], v[90:93]
	v_mfma_f32_16x16x32_bf16 v[78:81], v[134:137], v[230:233], v[78:81]
	v_mfma_f32_16x16x32_bf16 v[74:77], v[180:183], v[230:233], v[74:77]
	v_mfma_f32_16x16x32_bf16 v[118:121], v[184:187], v[202:205], v[118:121]
	v_mfma_f32_16x16x32_bf16 v[114:117], v[192:195], v[202:205], v[114:117]
	v_mfma_f32_16x16x32_bf16 v[102:105], v[184:187], v[210:213], v[102:105]
	v_mfma_f32_16x16x32_bf16 v[98:101], v[192:195], v[210:213], v[98:101]
	v_mfma_f32_16x16x32_bf16 v[86:89], v[184:187], v[218:221], v[86:89]
	v_mfma_f32_16x16x32_bf16 v[82:85], v[192:195], v[218:221], v[82:85]
	v_mfma_f32_16x16x32_bf16 v[70:73], v[184:187], v[226:229], v[70:73]
	v_mfma_f32_16x16x32_bf16 v[66:69], v[192:195], v[226:229], v[66:69]
	v_mfma_f32_16x16x32_bf16 v[118:121], v[188:191], v[206:209], v[118:121]
	v_mfma_f32_16x16x32_bf16 v[114:117], v[198:201], v[206:209], v[114:117]
	v_mfma_f32_16x16x32_bf16 v[102:105], v[188:191], v[214:217], v[102:105]
	v_mfma_f32_16x16x32_bf16 v[98:101], v[198:201], v[214:217], v[98:101]
	v_mfma_f32_16x16x32_bf16 v[86:89], v[188:191], v[222:225], v[86:89]
	v_mfma_f32_16x16x32_bf16 v[82:85], v[198:201], v[222:225], v[82:85]
	v_mfma_f32_16x16x32_bf16 v[70:73], v[188:191], v[230:233], v[70:73]
	v_mfma_f32_16x16x32_bf16 v[66:69], v[198:201], v[230:233], v[66:69]
	s_barrier
	s_setprio 0
	s_add_i32 s30, s69, s35
	s_mov_b32 m0, s30
	ds_read_b128 v[202:205], v178 offset:16384
	ds_read_b128 v[206:209], v178 offset:17408
	ds_read_b128 v[210:213], v178 offset:18432
	ds_read_b128 v[214:217], v178 offset:19456
	ds_read_b128 v[218:221], v178 offset:20480
	ds_read_b128 v[222:225], v178 offset:21504
	ds_read_b128 v[226:229], v178 offset:22528
	ds_read_b128 v[230:233], v178 offset:23552
	global_load_lds_dwordx4 v140, s[14:15]
	s_add_i32 m0, s30, 0x2000
	s_add_u32 s30, s14, 0x100000
	s_addc_u32 s31, s15, 0
	s_add_i32 s38, s70, s35
	global_load_lds_dwordx4 v144, s[14:15]
	s_mov_b32 m0, s38
	global_load_lds_dwordx4 v140, s[30:31]
	s_add_i32 m0, s38, 0x2000
	s_nop 0
	global_load_lds_dwordx4 v144, s[30:31]
	s_mov_b32 m0, s73
	s_nop 0
	global_load_lds_dwordx4 v138, s[18:19]
	s_mov_b32 m0, s66
	s_nop 0
	global_load_lds_dwordx4 v142, s[18:19]
	s_waitcnt vmcnt(8) lgkmcnt(0)
	s_setprio 1
	s_barrier
	v_mfma_f32_16x16x32_bf16 v[62:65], v[130:133], v[202:205], v[62:65]
	v_mfma_f32_16x16x32_bf16 v[58:61], v[170:173], v[202:205], v[58:61]
	v_mfma_f32_16x16x32_bf16 v[46:49], v[130:133], v[210:213], v[46:49]
	v_mfma_f32_16x16x32_bf16 v[42:45], v[170:173], v[210:213], v[42:45]
	v_mfma_f32_16x16x32_bf16 v[30:33], v[130:133], v[218:221], v[30:33]
	v_mfma_f32_16x16x32_bf16 v[26:29], v[170:173], v[218:221], v[26:29]
	v_mfma_f32_16x16x32_bf16 v[14:17], v[130:133], v[226:229], v[14:17]
	v_mfma_f32_16x16x32_bf16 v[10:13], v[170:173], v[226:229], v[10:13]
	v_mfma_f32_16x16x32_bf16 v[62:65], v[134:137], v[206:209], v[62:65]
	v_mfma_f32_16x16x32_bf16 v[58:61], v[180:183], v[206:209], v[58:61]
	v_mfma_f32_16x16x32_bf16 v[46:49], v[134:137], v[214:217], v[46:49]
	v_mfma_f32_16x16x32_bf16 v[42:45], v[180:183], v[214:217], v[42:45]
	v_mfma_f32_16x16x32_bf16 v[30:33], v[134:137], v[222:225], v[30:33]
	v_mfma_f32_16x16x32_bf16 v[26:29], v[180:183], v[222:225], v[26:29]
	v_mfma_f32_16x16x32_bf16 v[14:17], v[134:137], v[230:233], v[14:17]
	v_mfma_f32_16x16x32_bf16 v[10:13], v[180:183], v[230:233], v[10:13]
	v_mfma_f32_16x16x32_bf16 v[54:57], v[184:187], v[202:205], v[54:57]
	v_mfma_f32_16x16x32_bf16 v[50:53], v[192:195], v[202:205], v[50:53]
	v_mfma_f32_16x16x32_bf16 v[38:41], v[184:187], v[210:213], v[38:41]
	v_mfma_f32_16x16x32_bf16 v[34:37], v[192:195], v[210:213], v[34:37]
	v_mfma_f32_16x16x32_bf16 v[22:25], v[184:187], v[218:221], v[22:25]
	v_mfma_f32_16x16x32_bf16 v[18:21], v[192:195], v[218:221], v[18:21]
	v_mfma_f32_16x16x32_bf16 v[6:9], v[184:187], v[226:229], v[6:9]
	v_mfma_f32_16x16x32_bf16 v[2:5], v[192:195], v[226:229], v[2:5]
	v_mfma_f32_16x16x32_bf16 v[54:57], v[188:191], v[206:209], v[54:57]
	v_mfma_f32_16x16x32_bf16 v[50:53], v[198:201], v[206:209], v[50:53]
	v_mfma_f32_16x16x32_bf16 v[38:41], v[188:191], v[214:217], v[38:41]
	v_mfma_f32_16x16x32_bf16 v[34:37], v[198:201], v[214:217], v[34:37]
	v_mfma_f32_16x16x32_bf16 v[22:25], v[188:191], v[222:225], v[22:25]
	v_mfma_f32_16x16x32_bf16 v[18:21], v[198:201], v[222:225], v[18:21]
	v_mfma_f32_16x16x32_bf16 v[6:9], v[188:191], v[230:233], v[6:9]
	v_mfma_f32_16x16x32_bf16 v[2:5], v[198:201], v[230:233], v[2:5]
	s_barrier
	s_setprio 0
	s_add_i32 s30, 0, 0x18000
	s_add_i32 s31, 0, 0x1c000
	ds_read_b128 v[130:133], v176 offset:32768
	ds_read_b128 v[134:137], v176 offset:33792
	ds_read_b128 v[170:173], v176 offset:34816
	ds_read_b128 v[180:183], v176 offset:35840
	ds_read_b128 v[184:187], v176 offset:49152
	ds_read_b128 v[188:191], v176 offset:50176
	ds_read_b128 v[192:195], v176 offset:51200
	ds_read_b128 v[198:201], v176 offset:52224
	s_add_u32 s18, s18, 0x100000
	s_addc_u32 s19, s19, 0
	s_mov_b32 m0, s67
	ds_read_b128 v[202:205], v178 offset:32768
	ds_read_b128 v[206:209], v178 offset:33792
	ds_read_b128 v[210:213], v178 offset:34816
	ds_read_b128 v[214:217], v178 offset:35840
	ds_read_b128 v[218:221], v178 offset:36864
	ds_read_b128 v[222:225], v178 offset:37888
	ds_read_b128 v[226:229], v178 offset:38912
	ds_read_b128 v[230:233], v178 offset:39936
	global_load_lds_dwordx4 v138, s[18:19]
	s_mov_b32 m0, s88
	s_nop 0
	global_load_lds_dwordx4 v142, s[18:19]
	s_waitcnt vmcnt(8) lgkmcnt(0)
	s_setprio 1
	s_barrier
	v_mfma_f32_16x16x32_bf16 v[126:129], v[130:133], v[202:205], v[126:129]
	v_mfma_f32_16x16x32_bf16 v[122:125], v[170:173], v[202:205], v[122:125]
	v_mfma_f32_16x16x32_bf16 v[110:113], v[130:133], v[210:213], v[110:113]
	v_mfma_f32_16x16x32_bf16 v[106:109], v[170:173], v[210:213], v[106:109]
	v_mfma_f32_16x16x32_bf16 v[94:97], v[130:133], v[218:221], v[94:97]
	v_mfma_f32_16x16x32_bf16 v[90:93], v[170:173], v[218:221], v[90:93]
	v_mfma_f32_16x16x32_bf16 v[78:81], v[130:133], v[226:229], v[78:81]
	v_mfma_f32_16x16x32_bf16 v[74:77], v[170:173], v[226:229], v[74:77]
	v_mfma_f32_16x16x32_bf16 v[126:129], v[134:137], v[206:209], v[126:129]
	v_mfma_f32_16x16x32_bf16 v[122:125], v[180:183], v[206:209], v[122:125]
	v_mfma_f32_16x16x32_bf16 v[110:113], v[134:137], v[214:217], v[110:113]
	v_mfma_f32_16x16x32_bf16 v[106:109], v[180:183], v[214:217], v[106:109]
	v_mfma_f32_16x16x32_bf16 v[94:97], v[134:137], v[222:225], v[94:97]
	v_mfma_f32_16x16x32_bf16 v[90:93], v[180:183], v[222:225], v[90:93]
	v_mfma_f32_16x16x32_bf16 v[78:81], v[134:137], v[230:233], v[78:81]
	v_mfma_f32_16x16x32_bf16 v[74:77], v[180:183], v[230:233], v[74:77]
	v_mfma_f32_16x16x32_bf16 v[118:121], v[184:187], v[202:205], v[118:121]
	v_mfma_f32_16x16x32_bf16 v[114:117], v[192:195], v[202:205], v[114:117]
	v_mfma_f32_16x16x32_bf16 v[102:105], v[184:187], v[210:213], v[102:105]
	v_mfma_f32_16x16x32_bf16 v[98:101], v[192:195], v[210:213], v[98:101]
	v_mfma_f32_16x16x32_bf16 v[86:89], v[184:187], v[218:221], v[86:89]
	v_mfma_f32_16x16x32_bf16 v[82:85], v[192:195], v[218:221], v[82:85]
	v_mfma_f32_16x16x32_bf16 v[70:73], v[184:187], v[226:229], v[70:73]
	v_mfma_f32_16x16x32_bf16 v[66:69], v[192:195], v[226:229], v[66:69]
	v_mfma_f32_16x16x32_bf16 v[118:121], v[188:191], v[206:209], v[118:121]
	v_mfma_f32_16x16x32_bf16 v[114:117], v[198:201], v[206:209], v[114:117]
	v_mfma_f32_16x16x32_bf16 v[102:105], v[188:191], v[214:217], v[102:105]
	v_mfma_f32_16x16x32_bf16 v[98:101], v[198:201], v[214:217], v[98:101]
	v_mfma_f32_16x16x32_bf16 v[86:89], v[188:191], v[222:225], v[86:89]
	v_mfma_f32_16x16x32_bf16 v[82:85], v[198:201], v[222:225], v[82:85]
	v_mfma_f32_16x16x32_bf16 v[70:73], v[188:191], v[230:233], v[70:73]
	v_mfma_f32_16x16x32_bf16 v[66:69], v[198:201], v[230:233], v[66:69]
	s_barrier
	s_setprio 0
	s_add_u32 s14, s14, 0x80
	s_addc_u32 s15, s15, 0
	s_add_i32 m0, s35, 0x18000
	ds_read_b128 v[202:205], v178 offset:49152
	ds_read_b128 v[206:209], v178 offset:50176
	ds_read_b128 v[210:213], v178 offset:51200
	ds_read_b128 v[214:217], v178 offset:52224
	ds_read_b128 v[218:221], v178 offset:53248
	ds_read_b128 v[222:225], v178 offset:54272
	ds_read_b128 v[226:229], v178 offset:55296
	ds_read_b128 v[230:233], v178 offset:56320
	global_load_lds_dwordx4 v140, s[14:15]
	s_add_i32 m0, s35, 0x1a000
	s_add_u32 s18, s18, 0xfff00080
	global_load_lds_dwordx4 v144, s[14:15]
	s_addc_u32 s19, s19, -1
	s_add_u32 s14, s14, 0x100000
	s_addc_u32 s15, s15, 0
	s_add_i32 m0, s35, 0x1c000
	s_nop 0
	global_load_lds_dwordx4 v140, s[14:15]
	s_add_i32 m0, s35, 0x1e000
	s_nop 0
	global_load_lds_dwordx4 v144, s[14:15]
	s_mov_b32 m0, s89
	s_nop 0
	global_load_lds_dwordx4 v138, s[18:19]
	s_mov_b32 m0, s68
	s_nop 0
	global_load_lds_dwordx4 v142, s[18:19]
	s_waitcnt vmcnt(8) lgkmcnt(0)
	s_setprio 1
	s_barrier
	v_mfma_f32_16x16x32_bf16 v[62:65], v[130:133], v[202:205], v[62:65]
	v_mfma_f32_16x16x32_bf16 v[58:61], v[170:173], v[202:205], v[58:61]
	v_mfma_f32_16x16x32_bf16 v[46:49], v[130:133], v[210:213], v[46:49]
	v_mfma_f32_16x16x32_bf16 v[42:45], v[170:173], v[210:213], v[42:45]
	v_mfma_f32_16x16x32_bf16 v[30:33], v[130:133], v[218:221], v[30:33]
	v_mfma_f32_16x16x32_bf16 v[26:29], v[170:173], v[218:221], v[26:29]
	v_mfma_f32_16x16x32_bf16 v[14:17], v[130:133], v[226:229], v[14:17]
	v_mfma_f32_16x16x32_bf16 v[10:13], v[170:173], v[226:229], v[10:13]
	v_mfma_f32_16x16x32_bf16 v[62:65], v[134:137], v[206:209], v[62:65]
	v_mfma_f32_16x16x32_bf16 v[58:61], v[180:183], v[206:209], v[58:61]
	v_mfma_f32_16x16x32_bf16 v[46:49], v[134:137], v[214:217], v[46:49]
	v_mfma_f32_16x16x32_bf16 v[42:45], v[180:183], v[214:217], v[42:45]
	v_mfma_f32_16x16x32_bf16 v[30:33], v[134:137], v[222:225], v[30:33]
	v_mfma_f32_16x16x32_bf16 v[26:29], v[180:183], v[222:225], v[26:29]
	v_mfma_f32_16x16x32_bf16 v[14:17], v[134:137], v[230:233], v[14:17]
	v_mfma_f32_16x16x32_bf16 v[10:13], v[180:183], v[230:233], v[10:13]
	v_mfma_f32_16x16x32_bf16 v[54:57], v[184:187], v[202:205], v[54:57]
	v_mfma_f32_16x16x32_bf16 v[50:53], v[192:195], v[202:205], v[50:53]
	v_mfma_f32_16x16x32_bf16 v[38:41], v[184:187], v[210:213], v[38:41]
	v_mfma_f32_16x16x32_bf16 v[34:37], v[192:195], v[210:213], v[34:37]
	v_mfma_f32_16x16x32_bf16 v[22:25], v[184:187], v[218:221], v[22:25]
	v_mfma_f32_16x16x32_bf16 v[18:21], v[192:195], v[218:221], v[18:21]
	v_mfma_f32_16x16x32_bf16 v[6:9], v[184:187], v[226:229], v[6:9]
	v_mfma_f32_16x16x32_bf16 v[2:5], v[192:195], v[226:229], v[2:5]
	v_mfma_f32_16x16x32_bf16 v[54:57], v[188:191], v[206:209], v[54:57]
	v_mfma_f32_16x16x32_bf16 v[50:53], v[198:201], v[206:209], v[50:53]
	v_mfma_f32_16x16x32_bf16 v[38:41], v[188:191], v[214:217], v[38:41]
	v_mfma_f32_16x16x32_bf16 v[34:37], v[198:201], v[214:217], v[34:37]
	v_mfma_f32_16x16x32_bf16 v[22:25], v[188:191], v[222:225], v[22:25]
	v_mfma_f32_16x16x32_bf16 v[18:21], v[198:201], v[222:225], v[18:21]
	v_mfma_f32_16x16x32_bf16 v[6:9], v[188:191], v[230:233], v[6:9]
	v_mfma_f32_16x16x32_bf16 v[2:5], v[198:201], v[230:233], v[2:5]
	s_barrier
	s_setprio 0
	s_add_i32 s29, s29, 2
	s_add_u32 s8, s8, 0x100
	s_addc_u32 s9, s9, 0
	s_add_u32 s21, s21, 0x100
	s_addc_u32 s28, s28, 0
	s_cmp_gt_u32 s29, 61
	s_cbranch_scc0 .LBB0_126
	v_readlane_b32 s8, v249, 56
	v_readlane_b32 s9, v249, 57
	s_and_b64 vcc, exec, s[8:9]
	s_cbranch_vccz .LBB0_129
	s_barrier

.LBB0_678:
	ds_read_b128 v[148:151], v159
	ds_read_b128 v[152:155], v159 offset:1024
	ds_read_b128 v[164:167], v159 offset:2048
	ds_read_b128 v[168:171], v159 offset:3072
	ds_read_b128 v[172:175], v160
	ds_read_b128 v[176:179], v160 offset:1024
	ds_read_b128 v[180:183], v160 offset:2048
	ds_read_b128 v[184:187], v160 offset:3072
	s_add_u32 s60, s58, 0xfff00080
	s_addc_u32 s61, s59, -1
	s_cmp_eq_u32 s78, 60
	s_cselect_b32 s63, s7, s61
	s_cselect_b32 s62, s47, s60
	s_cselect_b32 s61, s45, s77
	s_cselect_b32 s60, s57, s76
	s_add_i32 m0, s64, 0xc000
	ds_read_b128 v[188:191], v161
	ds_read_b128 v[192:195], v161 offset:1024
	ds_read_b128 v[198:201], v161 offset:2048
	ds_read_b128 v[202:205], v161 offset:3072
	ds_read_b128 v[206:209], v161 offset:4096
	ds_read_b128 v[210:213], v161 offset:5120
	ds_read_b128 v[214:217], v161 offset:6144
	ds_read_b128 v[218:221], v161 offset:7168
	global_load_lds_dwordx4 v140, s[58:59]
	s_add_i32 m0, s64, 0xe000
	s_nop 0
	global_load_lds_dwordx4 v142, s[58:59]
	s_waitcnt vmcnt(8) lgkmcnt(0)
	s_setprio 1
	s_barrier
	v_mfma_f32_16x16x32_bf16 v[126:129], v[148:151], v[188:191], v[126:129]
	v_mfma_f32_16x16x32_bf16 v[122:125], v[164:167], v[188:191], v[122:125]
	v_mfma_f32_16x16x32_bf16 v[110:113], v[148:151], v[198:201], v[110:113]
	v_mfma_f32_16x16x32_bf16 v[106:109], v[164:167], v[198:201], v[106:109]
	v_mfma_f32_16x16x32_bf16 v[94:97], v[148:151], v[206:209], v[94:97]
	v_mfma_f32_16x16x32_bf16 v[90:93], v[164:167], v[206:209], v[90:93]
	v_mfma_f32_16x16x32_bf16 v[78:81], v[148:151], v[214:217], v[78:81]
	v_mfma_f32_16x16x32_bf16 v[74:77], v[164:167], v[214:217], v[74:77]
	v_mfma_f32_16x16x32_bf16 v[126:129], v[152:155], v[192:195], v[126:129]
	v_mfma_f32_16x16x32_bf16 v[122:125], v[168:171], v[192:195], v[122:125]
	v_mfma_f32_16x16x32_bf16 v[110:113], v[152:155], v[202:205], v[110:113]
	v_mfma_f32_16x16x32_bf16 v[106:109], v[168:171], v[202:205], v[106:109]
	v_mfma_f32_16x16x32_bf16 v[94:97], v[152:155], v[210:213], v[94:97]
	v_mfma_f32_16x16x32_bf16 v[90:93], v[168:171], v[210:213], v[90:93]
	v_mfma_f32_16x16x32_bf16 v[78:81], v[152:155], v[218:221], v[78:81]
	v_mfma_f32_16x16x32_bf16 v[74:77], v[168:171], v[218:221], v[74:77]
	v_mfma_f32_16x16x32_bf16 v[118:121], v[172:175], v[188:191], v[118:121]
	v_mfma_f32_16x16x32_bf16 v[114:117], v[180:183], v[188:191], v[114:117]
	v_mfma_f32_16x16x32_bf16 v[102:105], v[172:175], v[198:201], v[102:105]
	v_mfma_f32_16x16x32_bf16 v[98:101], v[180:183], v[198:201], v[98:101]
	v_mfma_f32_16x16x32_bf16 v[86:89], v[172:175], v[206:209], v[86:89]
	v_mfma_f32_16x16x32_bf16 v[82:85], v[180:183], v[206:209], v[82:85]
	v_mfma_f32_16x16x32_bf16 v[70:73], v[172:175], v[214:217], v[70:73]
	v_mfma_f32_16x16x32_bf16 v[66:69], v[180:183], v[214:217], v[66:69]
	v_mfma_f32_16x16x32_bf16 v[118:121], v[176:179], v[192:195], v[118:121]
	v_mfma_f32_16x16x32_bf16 v[114:117], v[184:187], v[192:195], v[114:117]
	v_mfma_f32_16x16x32_bf16 v[102:105], v[176:179], v[202:205], v[102:105]
	v_mfma_f32_16x16x32_bf16 v[98:101], v[184:187], v[202:205], v[98:101]
	v_mfma_f32_16x16x32_bf16 v[86:89], v[176:179], v[210:213], v[86:89]
	v_mfma_f32_16x16x32_bf16 v[82:85], v[184:187], v[210:213], v[82:85]
	v_mfma_f32_16x16x32_bf16 v[70:73], v[176:179], v[218:221], v[70:73]
	v_mfma_f32_16x16x32_bf16 v[66:69], v[184:187], v[218:221], v[66:69]
	s_barrier
	s_setprio 0
	s_add_i32 s79, s74, s33
	s_mov_b32 m0, s79
	ds_read_b128 v[188:191], v161 offset:16384
	ds_read_b128 v[192:195], v161 offset:17408
	ds_read_b128 v[198:201], v161 offset:18432
	ds_read_b128 v[202:205], v161 offset:19456
	ds_read_b128 v[206:209], v161 offset:20480
	ds_read_b128 v[210:213], v161 offset:21504
	ds_read_b128 v[214:217], v161 offset:22528
	ds_read_b128 v[218:221], v161 offset:23552
	global_load_lds_dwordx4 v132, s[60:61]
	s_add_i32 m0, s79, 0x2000
	s_add_u32 s80, s60, 0x100000
	s_addc_u32 s81, s61, 0
	s_add_i32 s79, s75, s33
	global_load_lds_dwordx4 v136, s[60:61]
	s_mov_b32 m0, s79
	global_load_lds_dwordx4 v132, s[80:81]
	s_add_i32 m0, s79, 0x2000
	s_nop 0
	global_load_lds_dwordx4 v136, s[80:81]
	s_mov_b32 m0, s64
	s_nop 0
	global_load_lds_dwordx4 v130, s[62:63]
	s_mov_b32 m0, s65
	s_nop 0
	global_load_lds_dwordx4 v134, s[62:63]
	s_waitcnt vmcnt(8) lgkmcnt(0)
	s_setprio 1
	s_barrier
	v_mfma_f32_16x16x32_bf16 v[62:65], v[148:151], v[188:191], v[62:65]
	v_mfma_f32_16x16x32_bf16 v[58:61], v[164:167], v[188:191], v[58:61]
	v_mfma_f32_16x16x32_bf16 v[46:49], v[148:151], v[198:201], v[46:49]
	v_mfma_f32_16x16x32_bf16 v[42:45], v[164:167], v[198:201], v[42:45]
	v_mfma_f32_16x16x32_bf16 v[30:33], v[148:151], v[206:209], v[30:33]
	v_mfma_f32_16x16x32_bf16 v[26:29], v[164:167], v[206:209], v[26:29]
	v_mfma_f32_16x16x32_bf16 v[14:17], v[148:151], v[214:217], v[14:17]
	v_mfma_f32_16x16x32_bf16 v[10:13], v[164:167], v[214:217], v[10:13]
	v_mfma_f32_16x16x32_bf16 v[62:65], v[152:155], v[192:195], v[62:65]
	v_mfma_f32_16x16x32_bf16 v[58:61], v[168:171], v[192:195], v[58:61]
	v_mfma_f32_16x16x32_bf16 v[46:49], v[152:155], v[202:205], v[46:49]
	v_mfma_f32_16x16x32_bf16 v[42:45], v[168:171], v[202:205], v[42:45]
	v_mfma_f32_16x16x32_bf16 v[30:33], v[152:155], v[210:213], v[30:33]
	v_mfma_f32_16x16x32_bf16 v[26:29], v[168:171], v[210:213], v[26:29]
	v_mfma_f32_16x16x32_bf16 v[14:17], v[152:155], v[218:221], v[14:17]
	v_mfma_f32_16x16x32_bf16 v[10:13], v[168:171], v[218:221], v[10:13]
	v_mfma_f32_16x16x32_bf16 v[54:57], v[172:175], v[188:191], v[54:57]
	v_mfma_f32_16x16x32_bf16 v[50:53], v[180:183], v[188:191], v[50:53]
	v_mfma_f32_16x16x32_bf16 v[38:41], v[172:175], v[198:201], v[38:41]
	v_mfma_f32_16x16x32_bf16 v[34:37], v[180:183], v[198:201], v[34:37]
	v_mfma_f32_16x16x32_bf16 v[22:25], v[172:175], v[206:209], v[22:25]
	v_mfma_f32_16x16x32_bf16 v[18:21], v[180:183], v[206:209], v[18:21]
	v_mfma_f32_16x16x32_bf16 v[6:9], v[172:175], v[214:217], v[6:9]
	v_mfma_f32_16x16x32_bf16 v[2:5], v[180:183], v[214:217], v[2:5]
	v_mfma_f32_16x16x32_bf16 v[54:57], v[176:179], v[192:195], v[54:57]
	v_mfma_f32_16x16x32_bf16 v[50:53], v[184:187], v[192:195], v[50:53]
	v_mfma_f32_16x16x32_bf16 v[38:41], v[176:179], v[202:205], v[38:41]
	v_mfma_f32_16x16x32_bf16 v[34:37], v[184:187], v[202:205], v[34:37]
	v_mfma_f32_16x16x32_bf16 v[22:25], v[176:179], v[210:213], v[22:25]
	v_mfma_f32_16x16x32_bf16 v[18:21], v[184:187], v[210:213], v[18:21]
	v_mfma_f32_16x16x32_bf16 v[6:9], v[176:179], v[218:221], v[6:9]
	v_mfma_f32_16x16x32_bf16 v[2:5], v[184:187], v[218:221], v[2:5]
	s_barrier
	s_setprio 0
	s_add_i32 s79, 0, 0x18000
	s_add_i32 s80, 0, 0x1c000
	ds_read_b128 v[148:151], v159 offset:32768
	ds_read_b128 v[152:155], v159 offset:33792
	ds_read_b128 v[164:167], v159 offset:34816
	ds_read_b128 v[168:171], v159 offset:35840
	ds_read_b128 v[172:175], v159 offset:49152
	ds_read_b128 v[176:179], v159 offset:50176
	ds_read_b128 v[180:183], v159 offset:51200
	ds_read_b128 v[184:187], v159 offset:52224
	s_add_u32 s62, s62, 0x100000
	s_addc_u32 s63, s63, 0
	s_mov_b32 m0, s66
	ds_read_b128 v[188:191], v161 offset:32768
	ds_read_b128 v[192:195], v161 offset:33792
	ds_read_b128 v[198:201], v161 offset:34816
	ds_read_b128 v[202:205], v161 offset:35840
	ds_read_b128 v[206:209], v161 offset:36864
	ds_read_b128 v[210:213], v161 offset:37888
	ds_read_b128 v[214:217], v161 offset:38912
	ds_read_b128 v[218:221], v161 offset:39936
	global_load_lds_dwordx4 v130, s[62:63]
	s_mov_b32 m0, s67
	s_nop 0
	global_load_lds_dwordx4 v134, s[62:63]
	s_waitcnt vmcnt(8) lgkmcnt(0)
	s_setprio 1
	s_barrier
	v_mfma_f32_16x16x32_bf16 v[126:129], v[148:151], v[188:191], v[126:129]
	v_mfma_f32_16x16x32_bf16 v[122:125], v[164:167], v[188:191], v[122:125]
	v_mfma_f32_16x16x32_bf16 v[110:113], v[148:151], v[198:201], v[110:113]
	v_mfma_f32_16x16x32_bf16 v[106:109], v[164:167], v[198:201], v[106:109]
	v_mfma_f32_16x16x32_bf16 v[94:97], v[148:151], v[206:209], v[94:97]
	v_mfma_f32_16x16x32_bf16 v[90:93], v[164:167], v[206:209], v[90:93]
	v_mfma_f32_16x16x32_bf16 v[78:81], v[148:151], v[214:217], v[78:81]
	v_mfma_f32_16x16x32_bf16 v[74:77], v[164:167], v[214:217], v[74:77]
	v_mfma_f32_16x16x32_bf16 v[126:129], v[152:155], v[192:195], v[126:129]
	v_mfma_f32_16x16x32_bf16 v[122:125], v[168:171], v[192:195], v[122:125]
	v_mfma_f32_16x16x32_bf16 v[110:113], v[152:155], v[202:205], v[110:113]
	v_mfma_f32_16x16x32_bf16 v[106:109], v[168:171], v[202:205], v[106:109]
	v_mfma_f32_16x16x32_bf16 v[94:97], v[152:155], v[210:213], v[94:97]
	v_mfma_f32_16x16x32_bf16 v[90:93], v[168:171], v[210:213], v[90:93]
	v_mfma_f32_16x16x32_bf16 v[78:81], v[152:155], v[218:221], v[78:81]
	v_mfma_f32_16x16x32_bf16 v[74:77], v[168:171], v[218:221], v[74:77]
	v_mfma_f32_16x16x32_bf16 v[118:121], v[172:175], v[188:191], v[118:121]
	v_mfma_f32_16x16x32_bf16 v[114:117], v[180:183], v[188:191], v[114:117]
	v_mfma_f32_16x16x32_bf16 v[102:105], v[172:175], v[198:201], v[102:105]
	v_mfma_f32_16x16x32_bf16 v[98:101], v[180:183], v[198:201], v[98:101]
	v_mfma_f32_16x16x32_bf16 v[86:89], v[172:175], v[206:209], v[86:89]
	v_mfma_f32_16x16x32_bf16 v[82:85], v[180:183], v[206:209], v[82:85]
	v_mfma_f32_16x16x32_bf16 v[70:73], v[172:175], v[214:217], v[70:73]
	v_mfma_f32_16x16x32_bf16 v[66:69], v[180:183], v[214:217], v[66:69]
	v_mfma_f32_16x16x32_bf16 v[118:121], v[176:179], v[192:195], v[118:121]
	v_mfma_f32_16x16x32_bf16 v[114:117], v[184:187], v[192:195], v[114:117]
	v_mfma_f32_16x16x32_bf16 v[102:105], v[176:179], v[202:205], v[102:105]
	v_mfma_f32_16x16x32_bf16 v[98:101], v[184:187], v[202:205], v[98:101]
	v_mfma_f32_16x16x32_bf16 v[86:89], v[176:179], v[210:213], v[86:89]
	v_mfma_f32_16x16x32_bf16 v[82:85], v[184:187], v[210:213], v[82:85]
	v_mfma_f32_16x16x32_bf16 v[70:73], v[176:179], v[218:221], v[70:73]
	v_mfma_f32_16x16x32_bf16 v[66:69], v[184:187], v[218:221], v[66:69]
	s_barrier
	s_setprio 0
	s_add_u32 s60, s60, 0x80
	s_addc_u32 s61, s61, 0
	s_add_i32 m0, s33, 0x18000
	ds_read_b128 v[188:191], v161 offset:49152
	ds_read_b128 v[192:195], v161 offset:50176
	ds_read_b128 v[198:201], v161 offset:51200
	ds_read_b128 v[202:205], v161 offset:52224
	ds_read_b128 v[206:209], v161 offset:53248
	ds_read_b128 v[210:213], v161 offset:54272
	ds_read_b128 v[214:217], v161 offset:55296
	ds_read_b128 v[218:221], v161 offset:56320
	global_load_lds_dwordx4 v132, s[60:61]
	s_add_i32 m0, s33, 0x1a000
	s_add_u32 s62, s62, 0xfff00080
	global_load_lds_dwordx4 v136, s[60:61]
	s_addc_u32 s63, s63, -1
	s_add_u32 s60, s60, 0x100000
	s_addc_u32 s61, s61, 0
	s_add_i32 m0, s33, 0x1c000
	s_nop 0
	global_load_lds_dwordx4 v132, s[60:61]
	s_add_i32 m0, s33, 0x1e000
	s_nop 0
	global_load_lds_dwordx4 v136, s[60:61]
	s_mov_b32 m0, s69
	s_nop 0
	global_load_lds_dwordx4 v130, s[62:63]
	s_mov_b32 m0, s70
	s_nop 0
	global_load_lds_dwordx4 v134, s[62:63]
	s_waitcnt vmcnt(8) lgkmcnt(0)
	s_setprio 1
	s_barrier
	v_mfma_f32_16x16x32_bf16 v[62:65], v[148:151], v[188:191], v[62:65]
	v_mfma_f32_16x16x32_bf16 v[58:61], v[164:167], v[188:191], v[58:61]
	v_mfma_f32_16x16x32_bf16 v[46:49], v[148:151], v[198:201], v[46:49]
	v_mfma_f32_16x16x32_bf16 v[42:45], v[164:167], v[198:201], v[42:45]
	v_mfma_f32_16x16x32_bf16 v[30:33], v[148:151], v[206:209], v[30:33]
	v_mfma_f32_16x16x32_bf16 v[26:29], v[164:167], v[206:209], v[26:29]
	v_mfma_f32_16x16x32_bf16 v[14:17], v[148:151], v[214:217], v[14:17]
	v_mfma_f32_16x16x32_bf16 v[10:13], v[164:167], v[214:217], v[10:13]
	v_mfma_f32_16x16x32_bf16 v[62:65], v[152:155], v[192:195], v[62:65]
	v_mfma_f32_16x16x32_bf16 v[58:61], v[168:171], v[192:195], v[58:61]
	v_mfma_f32_16x16x32_bf16 v[46:49], v[152:155], v[202:205], v[46:49]
	v_mfma_f32_16x16x32_bf16 v[42:45], v[168:171], v[202:205], v[42:45]
	v_mfma_f32_16x16x32_bf16 v[30:33], v[152:155], v[210:213], v[30:33]
	v_mfma_f32_16x16x32_bf16 v[26:29], v[168:171], v[210:213], v[26:29]
	v_mfma_f32_16x16x32_bf16 v[14:17], v[152:155], v[218:221], v[14:17]
	v_mfma_f32_16x16x32_bf16 v[10:13], v[168:171], v[218:221], v[10:13]
	v_mfma_f32_16x16x32_bf16 v[54:57], v[172:175], v[188:191], v[54:57]
	v_mfma_f32_16x16x32_bf16 v[50:53], v[180:183], v[188:191], v[50:53]
	v_mfma_f32_16x16x32_bf16 v[38:41], v[172:175], v[198:201], v[38:41]
	v_mfma_f32_16x16x32_bf16 v[34:37], v[180:183], v[198:201], v[34:37]
	v_mfma_f32_16x16x32_bf16 v[22:25], v[172:175], v[206:209], v[22:25]
	v_mfma_f32_16x16x32_bf16 v[18:21], v[180:183], v[206:209], v[18:21]
	v_mfma_f32_16x16x32_bf16 v[6:9], v[172:175], v[214:217], v[6:9]
	v_mfma_f32_16x16x32_bf16 v[2:5], v[180:183], v[214:217], v[2:5]
	v_mfma_f32_16x16x32_bf16 v[54:57], v[176:179], v[192:195], v[54:57]
	v_mfma_f32_16x16x32_bf16 v[50:53], v[184:187], v[192:195], v[50:53]
	v_mfma_f32_16x16x32_bf16 v[38:41], v[176:179], v[202:205], v[38:41]
	v_mfma_f32_16x16x32_bf16 v[34:37], v[184:187], v[202:205], v[34:37]
	v_mfma_f32_16x16x32_bf16 v[22:25], v[176:179], v[210:213], v[22:25]
	v_mfma_f32_16x16x32_bf16 v[18:21], v[184:187], v[210:213], v[18:21]
	v_mfma_f32_16x16x32_bf16 v[6:9], v[176:179], v[218:221], v[6:9]
	v_mfma_f32_16x16x32_bf16 v[2:5], v[184:187], v[218:221], v[2:5]
	s_barrier
	s_setprio 0
	s_add_i32 s78, s78, 2
	s_add_u32 s58, s58, 0x100
	s_addc_u32 s59, s59, 0
	s_add_u32 s76, s76, 0x100
	s_addc_u32 s77, s77, 0
	s_cmp_gt_u32 s78, 61
	s_cbranch_scc0 .LBB0_678
	s_and_b64 vcc, exec, s[18:19]
	s_cbranch_vccz .LBB0_681
	s_barrier

.LBB0_807:
	ds_read_b128 v[154:157], v150
	ds_read_b128 v[158:161], v150 offset:1024
	ds_read_b128 v[162:165], v150 offset:2048
	ds_read_b128 v[166:169], v150 offset:3072
	ds_read_b128 v[170:173], v151
	ds_read_b128 v[174:177], v151 offset:1024
	ds_read_b128 v[178:181], v151 offset:2048
	ds_read_b128 v[182:185], v151 offset:3072
	s_add_u32 s44, s42, 0xfff00080
	s_addc_u32 s45, s43, -1
	s_cmp_eq_u32 s68, 60
	s_cselect_b32 s47, s35, s45
	s_cselect_b32 s46, s64, s44
	s_cselect_b32 s45, s31, s67
	s_cselect_b32 s44, s65, s66
	s_add_i32 m0, s41, 0xc000
	ds_read_b128 v[186:189], v152
	ds_read_b128 v[190:193], v152 offset:1024
	ds_read_b128 v[198:201], v152 offset:2048
	ds_read_b128 v[202:205], v152 offset:3072
	ds_read_b128 v[206:209], v152 offset:4096
	ds_read_b128 v[210:213], v152 offset:5120
	ds_read_b128 v[214:217], v152 offset:6144
	ds_read_b128 v[218:221], v152 offset:7168
	global_load_lds_dwordx4 v138, s[42:43]
	s_add_i32 m0, s41, 0xe000
	s_nop 0
	global_load_lds_dwordx4 v140, s[42:43]
	s_waitcnt vmcnt(8) lgkmcnt(0)
	s_setprio 1
	s_barrier
	v_mfma_f32_16x16x32_bf16 v[126:129], v[154:157], v[186:189], v[126:129]
	v_mfma_f32_16x16x32_bf16 v[122:125], v[162:165], v[186:189], v[122:125]
	v_mfma_f32_16x16x32_bf16 v[110:113], v[154:157], v[198:201], v[110:113]
	v_mfma_f32_16x16x32_bf16 v[106:109], v[162:165], v[198:201], v[106:109]
	v_mfma_f32_16x16x32_bf16 v[94:97], v[154:157], v[206:209], v[94:97]
	v_mfma_f32_16x16x32_bf16 v[90:93], v[162:165], v[206:209], v[90:93]
	v_mfma_f32_16x16x32_bf16 v[78:81], v[154:157], v[214:217], v[78:81]
	v_mfma_f32_16x16x32_bf16 v[74:77], v[162:165], v[214:217], v[74:77]
	v_mfma_f32_16x16x32_bf16 v[126:129], v[158:161], v[190:193], v[126:129]
	v_mfma_f32_16x16x32_bf16 v[122:125], v[166:169], v[190:193], v[122:125]
	v_mfma_f32_16x16x32_bf16 v[110:113], v[158:161], v[202:205], v[110:113]
	v_mfma_f32_16x16x32_bf16 v[106:109], v[166:169], v[202:205], v[106:109]
	v_mfma_f32_16x16x32_bf16 v[94:97], v[158:161], v[210:213], v[94:97]
	v_mfma_f32_16x16x32_bf16 v[90:93], v[166:169], v[210:213], v[90:93]
	v_mfma_f32_16x16x32_bf16 v[78:81], v[158:161], v[218:221], v[78:81]
	v_mfma_f32_16x16x32_bf16 v[74:77], v[166:169], v[218:221], v[74:77]
	v_mfma_f32_16x16x32_bf16 v[118:121], v[170:173], v[186:189], v[118:121]
	v_mfma_f32_16x16x32_bf16 v[114:117], v[178:181], v[186:189], v[114:117]
	v_mfma_f32_16x16x32_bf16 v[102:105], v[170:173], v[198:201], v[102:105]
	v_mfma_f32_16x16x32_bf16 v[98:101], v[178:181], v[198:201], v[98:101]
	v_mfma_f32_16x16x32_bf16 v[86:89], v[170:173], v[206:209], v[86:89]
	v_mfma_f32_16x16x32_bf16 v[82:85], v[178:181], v[206:209], v[82:85]
	v_mfma_f32_16x16x32_bf16 v[70:73], v[170:173], v[214:217], v[70:73]
	v_mfma_f32_16x16x32_bf16 v[66:69], v[178:181], v[214:217], v[66:69]
	v_mfma_f32_16x16x32_bf16 v[118:121], v[174:177], v[190:193], v[118:121]
	v_mfma_f32_16x16x32_bf16 v[114:117], v[182:185], v[190:193], v[114:117]
	v_mfma_f32_16x16x32_bf16 v[102:105], v[174:177], v[202:205], v[102:105]
	v_mfma_f32_16x16x32_bf16 v[98:101], v[182:185], v[202:205], v[98:101]
	v_mfma_f32_16x16x32_bf16 v[86:89], v[174:177], v[210:213], v[86:89]
	v_mfma_f32_16x16x32_bf16 v[82:85], v[182:185], v[210:213], v[82:85]
	v_mfma_f32_16x16x32_bf16 v[70:73], v[174:177], v[218:221], v[70:73]
	v_mfma_f32_16x16x32_bf16 v[66:69], v[182:185], v[218:221], v[66:69]
	s_barrier
	s_setprio 0
	s_add_i32 s69, s57, s33
	s_mov_b32 m0, s69
	ds_read_b128 v[186:189], v152 offset:16384
	ds_read_b128 v[190:193], v152 offset:17408
	ds_read_b128 v[198:201], v152 offset:18432
	ds_read_b128 v[202:205], v152 offset:19456
	ds_read_b128 v[206:209], v152 offset:20480
	ds_read_b128 v[210:213], v152 offset:21504
	ds_read_b128 v[214:217], v152 offset:22528
	ds_read_b128 v[218:221], v152 offset:23552
	global_load_lds_dwordx4 v132, s[44:45]
	s_add_i32 m0, s69, 0x2000
	s_add_u32 s70, s44, 0x100000
	s_addc_u32 s71, s45, 0
	s_add_i32 s69, s58, s33
	global_load_lds_dwordx4 v136, s[44:45]
	s_mov_b32 m0, s69
	global_load_lds_dwordx4 v132, s[70:71]
	s_add_i32 m0, s69, 0x2000
	s_nop 0
	global_load_lds_dwordx4 v136, s[70:71]
	s_mov_b32 m0, s41
	s_nop 0
	global_load_lds_dwordx4 v130, s[46:47]
	s_mov_b32 m0, s50
	s_nop 0
	global_load_lds_dwordx4 v134, s[46:47]
	s_waitcnt vmcnt(8) lgkmcnt(0)
	s_setprio 1
	s_barrier
	v_mfma_f32_16x16x32_bf16 v[62:65], v[154:157], v[186:189], v[62:65]
	v_mfma_f32_16x16x32_bf16 v[58:61], v[162:165], v[186:189], v[58:61]
	v_mfma_f32_16x16x32_bf16 v[46:49], v[154:157], v[198:201], v[46:49]
	v_mfma_f32_16x16x32_bf16 v[42:45], v[162:165], v[198:201], v[42:45]
	v_mfma_f32_16x16x32_bf16 v[30:33], v[154:157], v[206:209], v[30:33]
	v_mfma_f32_16x16x32_bf16 v[26:29], v[162:165], v[206:209], v[26:29]
	v_mfma_f32_16x16x32_bf16 v[14:17], v[154:157], v[214:217], v[14:17]
	v_mfma_f32_16x16x32_bf16 v[10:13], v[162:165], v[214:217], v[10:13]
	v_mfma_f32_16x16x32_bf16 v[62:65], v[158:161], v[190:193], v[62:65]
	v_mfma_f32_16x16x32_bf16 v[58:61], v[166:169], v[190:193], v[58:61]
	v_mfma_f32_16x16x32_bf16 v[46:49], v[158:161], v[202:205], v[46:49]
	v_mfma_f32_16x16x32_bf16 v[42:45], v[166:169], v[202:205], v[42:45]
	v_mfma_f32_16x16x32_bf16 v[30:33], v[158:161], v[210:213], v[30:33]
	v_mfma_f32_16x16x32_bf16 v[26:29], v[166:169], v[210:213], v[26:29]
	v_mfma_f32_16x16x32_bf16 v[14:17], v[158:161], v[218:221], v[14:17]
	v_mfma_f32_16x16x32_bf16 v[10:13], v[166:169], v[218:221], v[10:13]
	v_mfma_f32_16x16x32_bf16 v[54:57], v[170:173], v[186:189], v[54:57]
	v_mfma_f32_16x16x32_bf16 v[50:53], v[178:181], v[186:189], v[50:53]
	v_mfma_f32_16x16x32_bf16 v[38:41], v[170:173], v[198:201], v[38:41]
	v_mfma_f32_16x16x32_bf16 v[34:37], v[178:181], v[198:201], v[34:37]
	v_mfma_f32_16x16x32_bf16 v[22:25], v[170:173], v[206:209], v[22:25]
	v_mfma_f32_16x16x32_bf16 v[18:21], v[178:181], v[206:209], v[18:21]
	v_mfma_f32_16x16x32_bf16 v[6:9], v[170:173], v[214:217], v[6:9]
	v_mfma_f32_16x16x32_bf16 v[2:5], v[178:181], v[214:217], v[2:5]
	v_mfma_f32_16x16x32_bf16 v[54:57], v[174:177], v[190:193], v[54:57]
	v_mfma_f32_16x16x32_bf16 v[50:53], v[182:185], v[190:193], v[50:53]
	v_mfma_f32_16x16x32_bf16 v[38:41], v[174:177], v[202:205], v[38:41]
	v_mfma_f32_16x16x32_bf16 v[34:37], v[182:185], v[202:205], v[34:37]
	v_mfma_f32_16x16x32_bf16 v[22:25], v[174:177], v[210:213], v[22:25]
	v_mfma_f32_16x16x32_bf16 v[18:21], v[182:185], v[210:213], v[18:21]
	v_mfma_f32_16x16x32_bf16 v[6:9], v[174:177], v[218:221], v[6:9]
	v_mfma_f32_16x16x32_bf16 v[2:5], v[182:185], v[218:221], v[2:5]
	s_barrier
	s_setprio 0
	s_add_i32 s69, 0, 0x18000
	s_add_i32 s70, 0, 0x1c000
	ds_read_b128 v[154:157], v150 offset:32768
	ds_read_b128 v[158:161], v150 offset:33792
	ds_read_b128 v[162:165], v150 offset:34816
	ds_read_b128 v[166:169], v150 offset:35840
	ds_read_b128 v[170:173], v150 offset:49152
	ds_read_b128 v[174:177], v150 offset:50176
	ds_read_b128 v[178:181], v150 offset:51200
	ds_read_b128 v[182:185], v150 offset:52224
	s_add_u32 s46, s46, 0x100000
	s_addc_u32 s47, s47, 0
	s_mov_b32 m0, s51
	ds_read_b128 v[186:189], v152 offset:32768
	ds_read_b128 v[190:193], v152 offset:33792
	ds_read_b128 v[198:201], v152 offset:34816
	ds_read_b128 v[202:205], v152 offset:35840
	ds_read_b128 v[206:209], v152 offset:36864
	ds_read_b128 v[210:213], v152 offset:37888
	ds_read_b128 v[214:217], v152 offset:38912
	ds_read_b128 v[218:221], v152 offset:39936
	global_load_lds_dwordx4 v130, s[46:47]
	s_mov_b32 m0, s52
	s_nop 0
	global_load_lds_dwordx4 v134, s[46:47]
	s_waitcnt vmcnt(8) lgkmcnt(0)
	s_setprio 1
	s_barrier
	v_mfma_f32_16x16x32_bf16 v[126:129], v[154:157], v[186:189], v[126:129]
	v_mfma_f32_16x16x32_bf16 v[122:125], v[162:165], v[186:189], v[122:125]
	v_mfma_f32_16x16x32_bf16 v[110:113], v[154:157], v[198:201], v[110:113]
	v_mfma_f32_16x16x32_bf16 v[106:109], v[162:165], v[198:201], v[106:109]
	v_mfma_f32_16x16x32_bf16 v[94:97], v[154:157], v[206:209], v[94:97]
	v_mfma_f32_16x16x32_bf16 v[90:93], v[162:165], v[206:209], v[90:93]
	v_mfma_f32_16x16x32_bf16 v[78:81], v[154:157], v[214:217], v[78:81]
	v_mfma_f32_16x16x32_bf16 v[74:77], v[162:165], v[214:217], v[74:77]
	v_mfma_f32_16x16x32_bf16 v[126:129], v[158:161], v[190:193], v[126:129]
	v_mfma_f32_16x16x32_bf16 v[122:125], v[166:169], v[190:193], v[122:125]
	v_mfma_f32_16x16x32_bf16 v[110:113], v[158:161], v[202:205], v[110:113]
	v_mfma_f32_16x16x32_bf16 v[106:109], v[166:169], v[202:205], v[106:109]
	v_mfma_f32_16x16x32_bf16 v[94:97], v[158:161], v[210:213], v[94:97]
	v_mfma_f32_16x16x32_bf16 v[90:93], v[166:169], v[210:213], v[90:93]
	v_mfma_f32_16x16x32_bf16 v[78:81], v[158:161], v[218:221], v[78:81]
	v_mfma_f32_16x16x32_bf16 v[74:77], v[166:169], v[218:221], v[74:77]
	v_mfma_f32_16x16x32_bf16 v[118:121], v[170:173], v[186:189], v[118:121]
	v_mfma_f32_16x16x32_bf16 v[114:117], v[178:181], v[186:189], v[114:117]
	v_mfma_f32_16x16x32_bf16 v[102:105], v[170:173], v[198:201], v[102:105]
	v_mfma_f32_16x16x32_bf16 v[98:101], v[178:181], v[198:201], v[98:101]
	v_mfma_f32_16x16x32_bf16 v[86:89], v[170:173], v[206:209], v[86:89]
	v_mfma_f32_16x16x32_bf16 v[82:85], v[178:181], v[206:209], v[82:85]
	v_mfma_f32_16x16x32_bf16 v[70:73], v[170:173], v[214:217], v[70:73]
	v_mfma_f32_16x16x32_bf16 v[66:69], v[178:181], v[214:217], v[66:69]
	v_mfma_f32_16x16x32_bf16 v[118:121], v[174:177], v[190:193], v[118:121]
	v_mfma_f32_16x16x32_bf16 v[114:117], v[182:185], v[190:193], v[114:117]
	v_mfma_f32_16x16x32_bf16 v[102:105], v[174:177], v[202:205], v[102:105]
	v_mfma_f32_16x16x32_bf16 v[98:101], v[182:185], v[202:205], v[98:101]
	v_mfma_f32_16x16x32_bf16 v[86:89], v[174:177], v[210:213], v[86:89]
	v_mfma_f32_16x16x32_bf16 v[82:85], v[182:185], v[210:213], v[82:85]
	v_mfma_f32_16x16x32_bf16 v[70:73], v[174:177], v[218:221], v[70:73]
	v_mfma_f32_16x16x32_bf16 v[66:69], v[182:185], v[218:221], v[66:69]
	s_barrier
	s_setprio 0
	s_add_u32 s44, s44, 0x80
	s_addc_u32 s45, s45, 0
	s_add_i32 m0, s33, 0x18000
	ds_read_b128 v[186:189], v152 offset:49152
	ds_read_b128 v[190:193], v152 offset:50176
	ds_read_b128 v[198:201], v152 offset:51200
	ds_read_b128 v[202:205], v152 offset:52224
	ds_read_b128 v[206:209], v152 offset:53248
	ds_read_b128 v[210:213], v152 offset:54272
	ds_read_b128 v[214:217], v152 offset:55296
	ds_read_b128 v[218:221], v152 offset:56320
	global_load_lds_dwordx4 v132, s[44:45]
	s_add_i32 m0, s33, 0x1a000
	s_add_u32 s46, s46, 0xfff00080
	global_load_lds_dwordx4 v136, s[44:45]
	s_addc_u32 s47, s47, -1
	s_add_u32 s44, s44, 0x100000
	s_addc_u32 s45, s45, 0
	s_add_i32 m0, s33, 0x1c000
	s_nop 0
	global_load_lds_dwordx4 v132, s[44:45]
	s_add_i32 m0, s33, 0x1e000
	s_nop 0
	global_load_lds_dwordx4 v136, s[44:45]
	s_mov_b32 m0, s55
	s_nop 0
	global_load_lds_dwordx4 v130, s[46:47]
	s_mov_b32 m0, s56
	s_nop 0
	global_load_lds_dwordx4 v134, s[46:47]
	s_waitcnt vmcnt(8) lgkmcnt(0)
	s_setprio 1
	s_barrier
	v_mfma_f32_16x16x32_bf16 v[62:65], v[154:157], v[186:189], v[62:65]
	v_mfma_f32_16x16x32_bf16 v[58:61], v[162:165], v[186:189], v[58:61]
	v_mfma_f32_16x16x32_bf16 v[46:49], v[154:157], v[198:201], v[46:49]
	v_mfma_f32_16x16x32_bf16 v[42:45], v[162:165], v[198:201], v[42:45]
	v_mfma_f32_16x16x32_bf16 v[30:33], v[154:157], v[206:209], v[30:33]
	v_mfma_f32_16x16x32_bf16 v[26:29], v[162:165], v[206:209], v[26:29]
	v_mfma_f32_16x16x32_bf16 v[14:17], v[154:157], v[214:217], v[14:17]
	v_mfma_f32_16x16x32_bf16 v[10:13], v[162:165], v[214:217], v[10:13]
	v_mfma_f32_16x16x32_bf16 v[62:65], v[158:161], v[190:193], v[62:65]
	v_mfma_f32_16x16x32_bf16 v[58:61], v[166:169], v[190:193], v[58:61]
	v_mfma_f32_16x16x32_bf16 v[46:49], v[158:161], v[202:205], v[46:49]
	v_mfma_f32_16x16x32_bf16 v[42:45], v[166:169], v[202:205], v[42:45]
	v_mfma_f32_16x16x32_bf16 v[30:33], v[158:161], v[210:213], v[30:33]
	v_mfma_f32_16x16x32_bf16 v[26:29], v[166:169], v[210:213], v[26:29]
	v_mfma_f32_16x16x32_bf16 v[14:17], v[158:161], v[218:221], v[14:17]
	v_mfma_f32_16x16x32_bf16 v[10:13], v[166:169], v[218:221], v[10:13]
	v_mfma_f32_16x16x32_bf16 v[54:57], v[170:173], v[186:189], v[54:57]
	v_mfma_f32_16x16x32_bf16 v[50:53], v[178:181], v[186:189], v[50:53]
	v_mfma_f32_16x16x32_bf16 v[38:41], v[170:173], v[198:201], v[38:41]
	v_mfma_f32_16x16x32_bf16 v[34:37], v[178:181], v[198:201], v[34:37]
	v_mfma_f32_16x16x32_bf16 v[22:25], v[170:173], v[206:209], v[22:25]
	v_mfma_f32_16x16x32_bf16 v[18:21], v[178:181], v[206:209], v[18:21]
	v_mfma_f32_16x16x32_bf16 v[6:9], v[170:173], v[214:217], v[6:9]
	v_mfma_f32_16x16x32_bf16 v[2:5], v[178:181], v[214:217], v[2:5]
	v_mfma_f32_16x16x32_bf16 v[54:57], v[174:177], v[190:193], v[54:57]
	v_mfma_f32_16x16x32_bf16 v[50:53], v[182:185], v[190:193], v[50:53]
	v_mfma_f32_16x16x32_bf16 v[38:41], v[174:177], v[202:205], v[38:41]
	v_mfma_f32_16x16x32_bf16 v[34:37], v[182:185], v[202:205], v[34:37]
	v_mfma_f32_16x16x32_bf16 v[22:25], v[174:177], v[210:213], v[22:25]
	v_mfma_f32_16x16x32_bf16 v[18:21], v[182:185], v[210:213], v[18:21]
	v_mfma_f32_16x16x32_bf16 v[6:9], v[174:177], v[218:221], v[6:9]
	v_mfma_f32_16x16x32_bf16 v[2:5], v[182:185], v[218:221], v[2:5]
	s_barrier
	s_setprio 0
	s_add_i32 s68, s68, 2
	s_add_u32 s42, s42, 0x100
	s_addc_u32 s43, s43, 0
	s_add_u32 s66, s66, 0x100
	s_addc_u32 s67, s67, 0
	s_cmp_gt_u32 s68, 61
	s_cbranch_scc0 .LBB0_807
	s_and_b64 vcc, exec, s[14:15]
	s_cbranch_vccz .LBB0_810
	s_barrier

.LBB0_897:
	ds_read_b128 v[146:149], v156
	ds_read_b128 v[150:153], v156 offset:1024
	ds_read_b128 v[160:163], v156 offset:2048
	ds_read_b128 v[164:167], v156 offset:3072
	ds_read_b128 v[168:171], v157
	ds_read_b128 v[172:175], v157 offset:1024
	ds_read_b128 v[176:179], v157 offset:2048
	ds_read_b128 v[180:183], v157 offset:3072
	s_add_u32 s44, s42, 0xffc00080
	s_addc_u32 s45, s43, -1
	s_cmpk_eq_i32 s67, 0xfc
	s_cselect_b32 s47, s35, s45
	s_cselect_b32 s46, s63, s44
	s_cselect_b32 s45, s31, s66
	s_cselect_b32 s44, s64, s65
	s_add_i32 m0, s41, 0xc000
	ds_read_b128 v[184:187], v158
	ds_read_b128 v[188:191], v158 offset:1024
	ds_read_b128 v[192:195], v158 offset:2048
	ds_read_b128 v[198:201], v158 offset:3072
	ds_read_b128 v[202:205], v158 offset:4096
	ds_read_b128 v[206:209], v158 offset:5120
	ds_read_b128 v[210:213], v158 offset:6144
	ds_read_b128 v[214:217], v158 offset:7168
	global_load_lds_dwordx4 v138, s[42:43]
	s_add_i32 m0, s41, 0xe000
	s_nop 0
	global_load_lds_dwordx4 v140, s[42:43]
	s_waitcnt vmcnt(8) lgkmcnt(0)
	s_setprio 1
	s_barrier
	v_mfma_f32_16x16x32_bf16 v[126:129], v[146:149], v[184:187], v[126:129]
	v_mfma_f32_16x16x32_bf16 v[122:125], v[160:163], v[184:187], v[122:125]
	v_mfma_f32_16x16x32_bf16 v[110:113], v[146:149], v[192:195], v[110:113]
	v_mfma_f32_16x16x32_bf16 v[106:109], v[160:163], v[192:195], v[106:109]
	v_mfma_f32_16x16x32_bf16 v[94:97], v[146:149], v[202:205], v[94:97]
	v_mfma_f32_16x16x32_bf16 v[90:93], v[160:163], v[202:205], v[90:93]
	v_mfma_f32_16x16x32_bf16 v[78:81], v[146:149], v[210:213], v[78:81]
	v_mfma_f32_16x16x32_bf16 v[74:77], v[160:163], v[210:213], v[74:77]
	v_mfma_f32_16x16x32_bf16 v[126:129], v[150:153], v[188:191], v[126:129]
	v_mfma_f32_16x16x32_bf16 v[122:125], v[164:167], v[188:191], v[122:125]
	v_mfma_f32_16x16x32_bf16 v[110:113], v[150:153], v[198:201], v[110:113]
	v_mfma_f32_16x16x32_bf16 v[106:109], v[164:167], v[198:201], v[106:109]
	v_mfma_f32_16x16x32_bf16 v[94:97], v[150:153], v[206:209], v[94:97]
	v_mfma_f32_16x16x32_bf16 v[90:93], v[164:167], v[206:209], v[90:93]
	v_mfma_f32_16x16x32_bf16 v[78:81], v[150:153], v[214:217], v[78:81]
	v_mfma_f32_16x16x32_bf16 v[74:77], v[164:167], v[214:217], v[74:77]
	v_mfma_f32_16x16x32_bf16 v[118:121], v[168:171], v[184:187], v[118:121]
	v_mfma_f32_16x16x32_bf16 v[114:117], v[176:179], v[184:187], v[114:117]
	v_mfma_f32_16x16x32_bf16 v[102:105], v[168:171], v[192:195], v[102:105]
	v_mfma_f32_16x16x32_bf16 v[98:101], v[176:179], v[192:195], v[98:101]
	v_mfma_f32_16x16x32_bf16 v[86:89], v[168:171], v[202:205], v[86:89]
	v_mfma_f32_16x16x32_bf16 v[82:85], v[176:179], v[202:205], v[82:85]
	v_mfma_f32_16x16x32_bf16 v[70:73], v[168:171], v[210:213], v[70:73]
	v_mfma_f32_16x16x32_bf16 v[66:69], v[176:179], v[210:213], v[66:69]
	v_mfma_f32_16x16x32_bf16 v[118:121], v[172:175], v[188:191], v[118:121]
	v_mfma_f32_16x16x32_bf16 v[114:117], v[180:183], v[188:191], v[114:117]
	v_mfma_f32_16x16x32_bf16 v[102:105], v[172:175], v[198:201], v[102:105]
	v_mfma_f32_16x16x32_bf16 v[98:101], v[180:183], v[198:201], v[98:101]
	v_mfma_f32_16x16x32_bf16 v[86:89], v[172:175], v[206:209], v[86:89]
	v_mfma_f32_16x16x32_bf16 v[82:85], v[180:183], v[206:209], v[82:85]
	v_mfma_f32_16x16x32_bf16 v[70:73], v[172:175], v[214:217], v[70:73]
	v_mfma_f32_16x16x32_bf16 v[66:69], v[180:183], v[214:217], v[66:69]
	s_barrier
	s_setprio 0
	s_add_i32 s68, s56, s48
	s_mov_b32 m0, s68
	ds_read_b128 v[184:187], v158 offset:16384
	ds_read_b128 v[188:191], v158 offset:17408
	ds_read_b128 v[192:195], v158 offset:18432
	ds_read_b128 v[198:201], v158 offset:19456
	ds_read_b128 v[202:205], v158 offset:20480
	ds_read_b128 v[206:209], v158 offset:21504
	ds_read_b128 v[210:213], v158 offset:22528
	ds_read_b128 v[214:217], v158 offset:23552
	global_load_lds_dwordx4 v132, s[44:45]
	s_add_i32 m0, s68, 0x2000
	s_add_u32 s68, s44, 0x400000
	s_addc_u32 s69, s45, 0
	s_add_i32 s70, s57, s48
	global_load_lds_dwordx4 v136, s[44:45]
	s_mov_b32 m0, s70
	global_load_lds_dwordx4 v132, s[68:69]
	s_add_i32 m0, s70, 0x2000
	s_nop 0
	global_load_lds_dwordx4 v136, s[68:69]
	s_mov_b32 m0, s41
	s_nop 0
	global_load_lds_dwordx4 v130, s[46:47]
	s_mov_b32 m0, s49
	s_nop 0
	global_load_lds_dwordx4 v134, s[46:47]
	s_waitcnt vmcnt(8) lgkmcnt(0)
	s_setprio 1
	s_barrier
	v_mfma_f32_16x16x32_bf16 v[62:65], v[146:149], v[184:187], v[62:65]
	v_mfma_f32_16x16x32_bf16 v[58:61], v[160:163], v[184:187], v[58:61]
	v_mfma_f32_16x16x32_bf16 v[46:49], v[146:149], v[192:195], v[46:49]
	v_mfma_f32_16x16x32_bf16 v[42:45], v[160:163], v[192:195], v[42:45]
	v_mfma_f32_16x16x32_bf16 v[30:33], v[146:149], v[202:205], v[30:33]
	v_mfma_f32_16x16x32_bf16 v[26:29], v[160:163], v[202:205], v[26:29]
	v_mfma_f32_16x16x32_bf16 v[14:17], v[146:149], v[210:213], v[14:17]
	v_mfma_f32_16x16x32_bf16 v[10:13], v[160:163], v[210:213], v[10:13]
	v_mfma_f32_16x16x32_bf16 v[62:65], v[150:153], v[188:191], v[62:65]
	v_mfma_f32_16x16x32_bf16 v[58:61], v[164:167], v[188:191], v[58:61]
	v_mfma_f32_16x16x32_bf16 v[46:49], v[150:153], v[198:201], v[46:49]
	v_mfma_f32_16x16x32_bf16 v[42:45], v[164:167], v[198:201], v[42:45]
	v_mfma_f32_16x16x32_bf16 v[30:33], v[150:153], v[206:209], v[30:33]
	v_mfma_f32_16x16x32_bf16 v[26:29], v[164:167], v[206:209], v[26:29]
	v_mfma_f32_16x16x32_bf16 v[14:17], v[150:153], v[214:217], v[14:17]
	v_mfma_f32_16x16x32_bf16 v[10:13], v[164:167], v[214:217], v[10:13]
	v_mfma_f32_16x16x32_bf16 v[54:57], v[168:171], v[184:187], v[54:57]
	v_mfma_f32_16x16x32_bf16 v[50:53], v[176:179], v[184:187], v[50:53]
	v_mfma_f32_16x16x32_bf16 v[38:41], v[168:171], v[192:195], v[38:41]
	v_mfma_f32_16x16x32_bf16 v[34:37], v[176:179], v[192:195], v[34:37]
	v_mfma_f32_16x16x32_bf16 v[22:25], v[168:171], v[202:205], v[22:25]
	v_mfma_f32_16x16x32_bf16 v[18:21], v[176:179], v[202:205], v[18:21]
	v_mfma_f32_16x16x32_bf16 v[6:9], v[168:171], v[210:213], v[6:9]
	v_mfma_f32_16x16x32_bf16 v[2:5], v[176:179], v[210:213], v[2:5]
	v_mfma_f32_16x16x32_bf16 v[54:57], v[172:175], v[188:191], v[54:57]
	v_mfma_f32_16x16x32_bf16 v[50:53], v[180:183], v[188:191], v[50:53]
	v_mfma_f32_16x16x32_bf16 v[38:41], v[172:175], v[198:201], v[38:41]
	v_mfma_f32_16x16x32_bf16 v[34:37], v[180:183], v[198:201], v[34:37]
	v_mfma_f32_16x16x32_bf16 v[22:25], v[172:175], v[206:209], v[22:25]
	v_mfma_f32_16x16x32_bf16 v[18:21], v[180:183], v[206:209], v[18:21]
	v_mfma_f32_16x16x32_bf16 v[6:9], v[172:175], v[214:217], v[6:9]
	v_mfma_f32_16x16x32_bf16 v[2:5], v[180:183], v[214:217], v[2:5]
	s_barrier
	s_setprio 0
	s_add_i32 s68, 0, 0x18000
	s_add_i32 s69, 0, 0x1c000
	ds_read_b128 v[146:149], v156 offset:32768
	ds_read_b128 v[150:153], v156 offset:33792
	ds_read_b128 v[160:163], v156 offset:34816
	ds_read_b128 v[164:167], v156 offset:35840
	ds_read_b128 v[168:171], v156 offset:49152
	ds_read_b128 v[172:175], v156 offset:50176
	ds_read_b128 v[176:179], v156 offset:51200
	ds_read_b128 v[180:183], v156 offset:52224
	s_add_u32 s46, s46, 0x400000
	s_addc_u32 s47, s47, 0
	s_mov_b32 m0, s50
	ds_read_b128 v[184:187], v158 offset:32768
	ds_read_b128 v[188:191], v158 offset:33792
	ds_read_b128 v[192:195], v158 offset:34816
	ds_read_b128 v[198:201], v158 offset:35840
	ds_read_b128 v[202:205], v158 offset:36864
	ds_read_b128 v[206:209], v158 offset:37888
	ds_read_b128 v[210:213], v158 offset:38912
	ds_read_b128 v[214:217], v158 offset:39936
	global_load_lds_dwordx4 v130, s[46:47]
	s_mov_b32 m0, s51
	s_nop 0
	global_load_lds_dwordx4 v134, s[46:47]
	s_waitcnt vmcnt(8) lgkmcnt(0)
	s_setprio 1
	s_barrier
	v_mfma_f32_16x16x32_bf16 v[126:129], v[146:149], v[184:187], v[126:129]
	v_mfma_f32_16x16x32_bf16 v[122:125], v[160:163], v[184:187], v[122:125]
	v_mfma_f32_16x16x32_bf16 v[110:113], v[146:149], v[192:195], v[110:113]
	v_mfma_f32_16x16x32_bf16 v[106:109], v[160:163], v[192:195], v[106:109]
	v_mfma_f32_16x16x32_bf16 v[94:97], v[146:149], v[202:205], v[94:97]
	v_mfma_f32_16x16x32_bf16 v[90:93], v[160:163], v[202:205], v[90:93]
	v_mfma_f32_16x16x32_bf16 v[78:81], v[146:149], v[210:213], v[78:81]
	v_mfma_f32_16x16x32_bf16 v[74:77], v[160:163], v[210:213], v[74:77]
	v_mfma_f32_16x16x32_bf16 v[126:129], v[150:153], v[188:191], v[126:129]
	v_mfma_f32_16x16x32_bf16 v[122:125], v[164:167], v[188:191], v[122:125]
	v_mfma_f32_16x16x32_bf16 v[110:113], v[150:153], v[198:201], v[110:113]
	v_mfma_f32_16x16x32_bf16 v[106:109], v[164:167], v[198:201], v[106:109]
	v_mfma_f32_16x16x32_bf16 v[94:97], v[150:153], v[206:209], v[94:97]
	v_mfma_f32_16x16x32_bf16 v[90:93], v[164:167], v[206:209], v[90:93]
	v_mfma_f32_16x16x32_bf16 v[78:81], v[150:153], v[214:217], v[78:81]
	v_mfma_f32_16x16x32_bf16 v[74:77], v[164:167], v[214:217], v[74:77]
	v_mfma_f32_16x16x32_bf16 v[118:121], v[168:171], v[184:187], v[118:121]
	v_mfma_f32_16x16x32_bf16 v[114:117], v[176:179], v[184:187], v[114:117]
	v_mfma_f32_16x16x32_bf16 v[102:105], v[168:171], v[192:195], v[102:105]
	v_mfma_f32_16x16x32_bf16 v[98:101], v[176:179], v[192:195], v[98:101]
	v_mfma_f32_16x16x32_bf16 v[86:89], v[168:171], v[202:205], v[86:89]
	v_mfma_f32_16x16x32_bf16 v[82:85], v[176:179], v[202:205], v[82:85]
	v_mfma_f32_16x16x32_bf16 v[70:73], v[168:171], v[210:213], v[70:73]
	v_mfma_f32_16x16x32_bf16 v[66:69], v[176:179], v[210:213], v[66:69]
	v_mfma_f32_16x16x32_bf16 v[118:121], v[172:175], v[188:191], v[118:121]
	v_mfma_f32_16x16x32_bf16 v[114:117], v[180:183], v[188:191], v[114:117]
	v_mfma_f32_16x16x32_bf16 v[102:105], v[172:175], v[198:201], v[102:105]
	v_mfma_f32_16x16x32_bf16 v[98:101], v[180:183], v[198:201], v[98:101]
	v_mfma_f32_16x16x32_bf16 v[86:89], v[172:175], v[206:209], v[86:89]
	v_mfma_f32_16x16x32_bf16 v[82:85], v[180:183], v[206:209], v[82:85]
	v_mfma_f32_16x16x32_bf16 v[70:73], v[172:175], v[214:217], v[70:73]
	v_mfma_f32_16x16x32_bf16 v[66:69], v[180:183], v[214:217], v[66:69]
	s_barrier
	s_setprio 0
	s_add_u32 s44, s44, 0x80
	s_addc_u32 s45, s45, 0
	s_add_i32 m0, s48, 0x18000
	ds_read_b128 v[184:187], v158 offset:49152
	ds_read_b128 v[188:191], v158 offset:50176
	ds_read_b128 v[192:195], v158 offset:51200
	ds_read_b128 v[198:201], v158 offset:52224
	ds_read_b128 v[202:205], v158 offset:53248
	ds_read_b128 v[206:209], v158 offset:54272
	ds_read_b128 v[210:213], v158 offset:55296
	ds_read_b128 v[214:217], v158 offset:56320
	global_load_lds_dwordx4 v132, s[44:45]
	s_add_i32 m0, s48, 0x1a000
	s_add_u32 s46, s46, 0xffc00080
	global_load_lds_dwordx4 v136, s[44:45]
	s_addc_u32 s47, s47, -1
	s_add_u32 s44, s44, 0x400000
	s_addc_u32 s45, s45, 0
	s_add_i32 m0, s48, 0x1c000
	s_nop 0
	global_load_lds_dwordx4 v132, s[44:45]
	s_add_i32 m0, s48, 0x1e000
	s_nop 0
	global_load_lds_dwordx4 v136, s[44:45]
	s_mov_b32 m0, s53
	s_nop 0
	global_load_lds_dwordx4 v130, s[46:47]
	s_mov_b32 m0, s54
	s_nop 0
	global_load_lds_dwordx4 v134, s[46:47]
	s_waitcnt vmcnt(8) lgkmcnt(0)
	s_setprio 1
	s_barrier
	v_mfma_f32_16x16x32_bf16 v[62:65], v[146:149], v[184:187], v[62:65]
	v_mfma_f32_16x16x32_bf16 v[58:61], v[160:163], v[184:187], v[58:61]
	v_mfma_f32_16x16x32_bf16 v[46:49], v[146:149], v[192:195], v[46:49]
	v_mfma_f32_16x16x32_bf16 v[42:45], v[160:163], v[192:195], v[42:45]
	v_mfma_f32_16x16x32_bf16 v[30:33], v[146:149], v[202:205], v[30:33]
	v_mfma_f32_16x16x32_bf16 v[26:29], v[160:163], v[202:205], v[26:29]
	v_mfma_f32_16x16x32_bf16 v[14:17], v[146:149], v[210:213], v[14:17]
	v_mfma_f32_16x16x32_bf16 v[10:13], v[160:163], v[210:213], v[10:13]
	v_mfma_f32_16x16x32_bf16 v[62:65], v[150:153], v[188:191], v[62:65]
	v_mfma_f32_16x16x32_bf16 v[58:61], v[164:167], v[188:191], v[58:61]
	v_mfma_f32_16x16x32_bf16 v[46:49], v[150:153], v[198:201], v[46:49]
	v_mfma_f32_16x16x32_bf16 v[42:45], v[164:167], v[198:201], v[42:45]
	v_mfma_f32_16x16x32_bf16 v[30:33], v[150:153], v[206:209], v[30:33]
	v_mfma_f32_16x16x32_bf16 v[26:29], v[164:167], v[206:209], v[26:29]
	v_mfma_f32_16x16x32_bf16 v[14:17], v[150:153], v[214:217], v[14:17]
	v_mfma_f32_16x16x32_bf16 v[10:13], v[164:167], v[214:217], v[10:13]
	v_mfma_f32_16x16x32_bf16 v[54:57], v[168:171], v[184:187], v[54:57]
	v_mfma_f32_16x16x32_bf16 v[50:53], v[176:179], v[184:187], v[50:53]
	v_mfma_f32_16x16x32_bf16 v[38:41], v[168:171], v[192:195], v[38:41]
	v_mfma_f32_16x16x32_bf16 v[34:37], v[176:179], v[192:195], v[34:37]
	v_mfma_f32_16x16x32_bf16 v[22:25], v[168:171], v[202:205], v[22:25]
	v_mfma_f32_16x16x32_bf16 v[18:21], v[176:179], v[202:205], v[18:21]
	v_mfma_f32_16x16x32_bf16 v[6:9], v[168:171], v[210:213], v[6:9]
	v_mfma_f32_16x16x32_bf16 v[2:5], v[176:179], v[210:213], v[2:5]
	v_mfma_f32_16x16x32_bf16 v[54:57], v[172:175], v[188:191], v[54:57]
	v_mfma_f32_16x16x32_bf16 v[50:53], v[180:183], v[188:191], v[50:53]
	v_mfma_f32_16x16x32_bf16 v[38:41], v[172:175], v[198:201], v[38:41]
	v_mfma_f32_16x16x32_bf16 v[34:37], v[180:183], v[198:201], v[34:37]
	v_mfma_f32_16x16x32_bf16 v[22:25], v[172:175], v[206:209], v[22:25]
	v_mfma_f32_16x16x32_bf16 v[18:21], v[180:183], v[206:209], v[18:21]
	v_mfma_f32_16x16x32_bf16 v[6:9], v[172:175], v[214:217], v[6:9]
	v_mfma_f32_16x16x32_bf16 v[2:5], v[180:183], v[214:217], v[2:5]
	s_barrier
	s_setprio 0
	s_add_i32 s67, s67, 2
	s_add_u32 s42, s42, 0x100
	s_addc_u32 s43, s43, 0
	s_add_u32 s65, s65, 0x100
	s_addc_u32 s66, s66, 0
	s_cmpk_gt_u32 s67, 0xfd
	s_cbranch_scc0 .LBB0_897
	s_and_b64 vcc, exec, s[14:15]
	s_cbranch_vccz .LBB0_900
	s_barrier
